# v16 + ctx skinny GEMM: 16 operand loads per k-iteration issued together with counted vmcnt waits (was 8 serialized flat-load round trips per iteration)
# baseline (speedup 1.0000x reference)
; __device__ __forceinline__ void ctx_gemm(LAS unsigned char* lds, const bf16_t* A, int lda, const bf16_t* Bt, int K, bf16_t* Y) {
;     ...
;         for (int k0 = 0; k0 < kw; k0 += 64) {
;             bf16x8 af[2][4], bf[2][4];
; #pragma unroll
;             for (int u = 0; u < 2; ++u)
; #pragma unroll
;                 for (int i = 0; i < 4; ++i) { af[u][i] = *(const bf16x8*)(ap + (size_t)(16 * i) * lda + k0 + 32 * u); bf[u][i] = *(const bf16x8*)(bp + (size_t)(16 * i) * K + k0 + 32 * u); }
; #pragma unroll
;             for (int u = 0; u < 2; ++u)
; #pragma unroll
;                 for (int i = 0; i < 4; ++i)
; #pragma unroll
;                     for (int j = 0; j < 4; ++j) acc[i][j] = __builtin_amdgcn_mfma_f32_16x16x32_bf16(bf[u][j], af[u][i], acc[i][j], 0, 0, 0);
;         }
.LBB0_537:
	s_waitcnt vmcnt(0)
	v_lshl_add_u64 v[154:155], v[94:95], 0, s[38:39]
	v_lshl_add_u64 v[158:159], v[92:93], 0, s[38:39]
	v_lshl_add_u64 v[160:161], v[90:91], 0, s[38:39]
	v_lshl_add_u64 v[162:163], v[88:89], 0, s[38:39]
	v_lshl_add_u64 v[152:153], v[80:81], 0, s[38:39]
	v_lshl_add_u64 v[156:157], v[82:83], 0, s[38:39]
	v_lshl_add_u64 v[164:165], v[84:85], 0, s[38:39]
	v_lshl_add_u64 v[166:167], v[86:87], 0, s[38:39]
	global_load_dwordx4 v[132:135], v[154:155], off
	global_load_dwordx4 v[140:143], v[158:159], off
	global_load_dwordx4 v[144:147], v[160:161], off
	global_load_dwordx4 v[148:151], v[162:163], off
	global_load_dwordx4 v[136:139], v[152:153], off
	global_load_dwordx4 v[168:171], v[156:157], off
	global_load_dwordx4 v[172:175], v[164:165], off
	global_load_dwordx4 v[184:187], v[166:167], off
	global_load_dwordx4 v[188:191], v[154:155], off offset:64
	global_load_dwordx4 v[192:195], v[158:159], off offset:64
	global_load_dwordx4 v[196:199], v[160:161], off offset:64
	global_load_dwordx4 v[200:203], v[162:163], off offset:64
	global_load_dwordx4 v[208:211], v[152:153], off offset:64
	global_load_dwordx4 v[224:227], v[156:157], off offset:64
	global_load_dwordx4 v[228:231], v[164:165], off offset:64
	global_load_dwordx4 v[232:235], v[166:167], off offset:64
	s_add_i32 s14, s14, 64
	v_lshl_add_u64 v[80:81], v[80:81], 0, s[4:5]
	v_lshl_add_u64 v[82:83], v[82:83], 0, s[4:5]
	v_lshl_add_u64 v[88:89], v[88:89], 0, s[4:5]
	v_lshl_add_u64 v[84:85], v[84:85], 0, s[4:5]
	v_lshl_add_u64 v[90:91], v[90:91], 0, s[4:5]
	v_lshl_add_u64 v[86:87], v[86:87], 0, s[4:5]
	v_lshl_add_u64 v[92:93], v[92:93], 0, s[4:5]
	v_lshl_add_u64 v[94:95], v[94:95], 0, s[4:5]
	s_cmp_ge_u32 s14, s29
	s_waitcnt vmcnt(11)
	v_mfma_f32_16x16x32_bf16 v[2:5], v[132:135], v[136:139], v[2:5]
	v_mfma_f32_16x16x32_bf16 v[6:9], v[140:143], v[136:139], v[6:9]
	v_mfma_f32_16x16x32_bf16 v[10:13], v[144:147], v[136:139], v[10:13]
	v_mfma_f32_16x16x32_bf16 v[30:33], v[148:151], v[136:139], v[30:33]
	s_waitcnt vmcnt(10)
	v_mfma_f32_16x16x32_bf16 v[26:29], v[132:135], v[168:171], v[26:29]
	v_mfma_f32_16x16x32_bf16 v[22:25], v[140:143], v[168:171], v[22:25]
	v_mfma_f32_16x16x32_bf16 v[18:21], v[144:147], v[168:171], v[18:21]
	v_mfma_f32_16x16x32_bf16 v[14:17], v[148:151], v[168:171], v[14:17]
	s_waitcnt vmcnt(9)
	v_mfma_f32_16x16x32_bf16 v[46:49], v[132:135], v[172:175], v[46:49]
	v_mfma_f32_16x16x32_bf16 v[42:45], v[140:143], v[172:175], v[42:45]
	v_mfma_f32_16x16x32_bf16 v[38:41], v[144:147], v[172:175], v[38:41]
	v_mfma_f32_16x16x32_bf16 v[34:37], v[148:151], v[172:175], v[34:37]
	s_waitcnt vmcnt(8)
	v_mfma_f32_16x16x32_bf16 v[50:53], v[132:135], v[184:187], v[50:53]
	v_mfma_f32_16x16x32_bf16 v[54:57], v[140:143], v[184:187], v[54:57]
	v_mfma_f32_16x16x32_bf16 v[62:65], v[144:147], v[184:187], v[62:65]
	v_mfma_f32_16x16x32_bf16 v[58:61], v[148:151], v[184:187], v[58:61]
	s_waitcnt vmcnt(3)
	v_mfma_f32_16x16x32_bf16 v[2:5], v[188:191], v[208:211], v[2:5]
	v_mfma_f32_16x16x32_bf16 v[6:9], v[192:195], v[208:211], v[6:9]
	v_mfma_f32_16x16x32_bf16 v[10:13], v[196:199], v[208:211], v[10:13]
	v_mfma_f32_16x16x32_bf16 v[30:33], v[200:203], v[208:211], v[30:33]
	s_waitcnt vmcnt(2)
	v_mfma_f32_16x16x32_bf16 v[26:29], v[188:191], v[224:227], v[26:29]
	v_mfma_f32_16x16x32_bf16 v[22:25], v[192:195], v[224:227], v[22:25]
	v_mfma_f32_16x16x32_bf16 v[18:21], v[196:199], v[224:227], v[18:21]
	v_mfma_f32_16x16x32_bf16 v[14:17], v[200:203], v[224:227], v[14:17]
	s_waitcnt vmcnt(1)
	v_mfma_f32_16x16x32_bf16 v[46:49], v[188:191], v[228:231], v[46:49]
	v_mfma_f32_16x16x32_bf16 v[42:45], v[192:195], v[228:231], v[42:45]
	v_mfma_f32_16x16x32_bf16 v[38:41], v[196:199], v[228:231], v[38:41]
	v_mfma_f32_16x16x32_bf16 v[34:37], v[200:203], v[228:231], v[34:37]
	s_waitcnt vmcnt(0)
	v_mfma_f32_16x16x32_bf16 v[50:53], v[188:191], v[232:235], v[50:53]
	v_mfma_f32_16x16x32_bf16 v[54:57], v[192:195], v[232:235], v[54:57]
	v_mfma_f32_16x16x32_bf16 v[62:65], v[196:199], v[232:235], v[62:65]
	v_mfma_f32_16x16x32_bf16 v[58:61], v[200:203], v[232:235], v[58:61]
	s_cbranch_scc0 .LBB0_537
	s_and_b64 vcc, exec, s[8:9]
	s_cbranch_vccz .LBB0_540
	ds_write_b128 v99, v[2:5]
	ds_write_b128 v100, v[6:9]
	ds_write_b128 v101, v[10:13]
	ds_write_b128 v102, v[30:33]
	ds_write_b128 v103, v[26:29]
	ds_write_b128 v104, v[22:25]
	ds_write_b128 v105, v[18:21]
	ds_write_b128 v106, v[14:17]
	ds_write_b128 v107, v[46:49]
	ds_write_b128 v108, v[42:45]
	ds_write_b128 v109, v[38:41]
	ds_write_b128 v110, v[34:37]
	ds_write_b128 v111, v[50:53]
	ds_write_b128 v112, v[54:57]
	ds_write_b128 v113, v[62:65]
	ds_write_b128 v114, v[58:61]
